# attention tile loop: swap the two MFMAs of 17 alternate same-K/V-fragment groups so consecutive groups share the B operand registers (on top of v55)
# speedup vs baseline: 1.0091x; 1.0037x over previous
; #define ATT_WAIT_BAR() asm volatile("s_waitcnt vmcnt(0) lgkmcnt(0)\n\ts_barrier" ::: "memory")
; #define ATT_SB() __builtin_amdgcn_sched_barrier(0)
; #define A16_VLD(v, g) do { const LAS unsigned char* a_ = vbp[(g) & 3] + vso + ((g) >> 4) * 16384 + (((g) & 15) >> 2) * 1024; v[0] = vtr(a_); v[1] = vtr(a_ + 8192); } while (0)
; #define A16_GAP(i) do { A16_EL(i) = __builtin_amdgcn_exp2f(A16_EL(i)); \
;                 if ((i) > 0) { if ((((i) - 1) >> 2) & 1) s1 += A16_EL((i) - 1); else s0 += A16_EL((i) - 1); } asm volatile("" : "+v"(s0), "+v"(s1)); } while (0)
; __device__ __forceinline__ void attn_core16(f32x4 (&O)[16][2], float (&lq)[2], const bf16_t* Qw, int q_pitch, const bf16_t* Kh, const bf16_t* Vh, int kv_pitch,
;                                             int NT, int nt_act, int kch0, float negb, LAS unsigned char* ring, int wid) {
;     ...
;         ATT_WAIT_BAR();
;         if (t < nt_act) {
;             const bool more = (t + 1 < nt_act);
;             const int vso = (t & 1) * SLOTB;
;             s16x4 vv[3][2];
;     ...
;             A16_VLD(vv[0], 0);
;             ATT_SB();
;             A16_QK(t + 1, 1, t);
;             ATT_SB();
;             A16_VLD(vv[1], 1);
;             float s0 = 0.f, s1 = 0.f;
;     ...
; #pragma unroll
;             for (int g = 0; g < 32; ++g) {
;                 if (g + 2 < 32) A16_VLD(vv[(g + 2) % 3], g + 2);
;                 ATT_SB();
;                 O[g & 15][0] = __builtin_amdgcn_mfma_f32_16x16x32_bf16(A16_VF(vv[g % 3]), __builtin_bit_cast(bf16x8, pw[g >> 4][0]), O[g & 15][0], 0, 0, 0);
;                 O[g & 15][1] = __builtin_amdgcn_mfma_f32_16x16x32_bf16(A16_VF(vv[g % 3]), __builtin_bit_cast(bf16x8, pw[g >> 4][1]), O[g & 15][1], 0, 0, 0);
;                 A16_GAP(g);
.LBB0_685:
	s_waitcnt vmcnt(0) lgkmcnt(0)
	s_barrier
	s_add_i32 s20, s0, 1
	s_cmp_ge_u32 s0, s73
	s_cbranch_scc1 .LBB0_687
	s_add_i32 s48, s72, 0xffff0000
	s_and_b32 s50, s48, 0x10000
	v_add_u32_e32 v0, s50, v216
	ds_read_b64_tr_b16 v[220:221], v0 offset:32768
	ds_read_b64_tr_b16 v[222:223], v0 offset:40960
	s_and_b32 s80, s72, 0x10000
	v_add_u32_e32 v2, s80, v214
	ds_read_b128 v[188:191], v2
	ds_read_b128 v[192:195], v2 offset:8192
	s_add_i32 s0, s0, 2
	s_min_u32 vcc_lo, s0, s21
	s_min_u32 s0, s20, s21
	s_lshl_b64 s[70:71], s[0:1], 18
	s_add_u32 s70, s38, s70
	s_mov_b32 vcc_hi, s1
	ds_read_b128 v[200:203], v2 offset:16384
	s_addc_u32 s71, s39, s71
	s_add_i32 s0, s12, s80
	s_lshl_b64 vcc, vcc, 18
	s_add_u32 s54, s18, vcc_lo
	s_addc_u32 s55, s19, vcc_hi
	s_add_i32 vcc_lo, s13, s50
	s_waitcnt lgkmcnt(2)
	v_mfma_f32_16x16x32_bf16 v[196:199], v[188:191], v[136:139], v[168:171]
	s_mov_b32 s48, m0
	s_mov_b32 m0, vcc_lo
	s_nop 0
	global_load_lds_dwordx4 v212, s[54:55]
	s_mov_b32 m0, s48
	v_mfma_f32_16x16x32_bf16 v[188:191], v[188:191], v[152:155], v[168:171]
	ds_read_b128 v[204:207], v2 offset:24576
	s_add_u32 s48, s54, 0x80
	s_waitcnt lgkmcnt(2)
	v_mfma_f32_16x16x32_bf16 v[224:227], v[192:195], v[136:139], v[168:171]
	s_addc_u32 s49, s55, 0
	s_add_i32 vcc_hi, vcc_lo, 0x400
	s_mov_b32 s9, m0
	s_mov_b32 m0, vcc_hi
	s_nop 0
	global_load_lds_dwordx4 v212, s[48:49]
	s_mov_b32 m0, s9
	v_mfma_f32_16x16x32_bf16 v[192:195], v[192:195], v[152:155], v[168:171]
	v_add_u32_e32 v3, s80, v215
	ds_read_b128 v[230:233], v3
	s_add_u32 s48, s54, 0x100
	s_waitcnt lgkmcnt(2)
	v_mfma_f32_16x16x32_bf16 v[234:237], v[200:203], v[136:139], v[168:171]
	s_addc_u32 s49, s55, 0
	s_add_i32 s9, vcc_lo, 0x800
	s_mov_b32 s80, m0
	s_mov_b32 m0, s9
	s_nop 0
	global_load_lds_dwordx4 v212, s[48:49]
	s_mov_b32 m0, s80
	v_mfma_f32_16x16x32_bf16 v[200:203], v[200:203], v[152:155], v[168:171]
	ds_read_b128 v[238:241], v3 offset:8192
	s_add_u32 s48, s54, 0x180
	s_waitcnt lgkmcnt(2)
	v_mfma_f32_16x16x32_bf16 v[242:245], v[204:207], v[136:139], v[168:171]
	s_addc_u32 s49, s55, 0
	s_add_i32 s9, vcc_lo, 0xc00
	s_mov_b32 s54, m0
	s_mov_b32 m0, s9
	s_nop 0
	global_load_lds_dwordx4 v212, s[48:49]
	s_mov_b32 m0, s54
	v_mfma_f32_16x16x32_bf16 v[204:207], v[204:207], v[152:155], v[168:171]
	ds_read_b128 v[246:249], v3 offset:16384
	s_waitcnt lgkmcnt(2)
	v_mfma_f32_16x16x32_bf16 v[196:199], v[230:233], v[140:143], v[196:199]
	s_mov_b32 s9, m0
	s_mov_b32 m0, s0
	s_nop 0
	global_load_lds_dwordx4 v213, s[70:71]
	s_mov_b32 m0, s9
	v_mfma_f32_16x16x32_bf16 v[188:191], v[230:233], v[156:159], v[188:191]
	ds_read_b128 v[230:233], v3 offset:24576
	s_add_u32 s48, s70, 0x80
	s_waitcnt lgkmcnt(2)
	v_mfma_f32_16x16x32_bf16 v[192:195], v[238:241], v[156:159], v[192:195]
	s_addc_u32 s49, s71, 0
	s_add_i32 s9, s0, 0x400
	s_mov_b32 s54, m0
	s_mov_b32 m0, s9
	s_nop 0
	global_load_lds_dwordx4 v213, s[48:49]
	s_mov_b32 m0, s54
	v_mfma_f32_16x16x32_bf16 v[224:227], v[238:241], v[140:143], v[224:227]
	ds_read_b128 v[238:241], v2 offset:1024
	s_add_u32 s48, s70, 0x100
	s_waitcnt lgkmcnt(2)
	v_mfma_f32_16x16x32_bf16 v[234:237], v[246:249], v[140:143], v[234:237]
	s_addc_u32 s49, s71, 0
	s_add_i32 s9, s0, 0x800
	s_mov_b32 s54, m0
	s_mov_b32 m0, s9
	s_nop 0
	global_load_lds_dwordx4 v213, s[48:49]
	s_mov_b32 m0, s54
	v_mfma_f32_16x16x32_bf16 v[200:203], v[246:249], v[156:159], v[200:203]
	ds_read_b128 v[246:249], v2 offset:9216
	s_add_u32 s48, s70, 0x180
	s_waitcnt lgkmcnt(2)
	v_mfma_f32_16x16x32_bf16 v[204:207], v[230:233], v[156:159], v[204:207]
	s_addc_u32 s49, s71, 0
	s_addk_i32 s0, 0xc00
	s_mov_b32 s9, m0
	s_mov_b32 m0, s0
	s_nop 0
	global_load_lds_dwordx4 v213, s[48:49]
	s_mov_b32 m0, s9
	v_mfma_f32_16x16x32_bf16 v[242:245], v[230:233], v[140:143], v[242:245]
	ds_read_b128 v[230:233], v2 offset:17408
	s_waitcnt lgkmcnt(2)
	v_mfma_f32_16x16x32_bf16 v[196:199], v[238:241], v[144:147], v[196:199]
	v_mfma_f32_16x16x32_bf16 v[188:191], v[238:241], v[160:163], v[188:191]
	ds_read_b128 v[238:241], v2 offset:25600
	s_waitcnt lgkmcnt(2)
	v_mfma_f32_16x16x32_bf16 v[192:195], v[246:249], v[160:163], v[192:195]
	v_mfma_f32_16x16x32_bf16 v[224:227], v[246:249], v[144:147], v[224:227]
	ds_read_b128 v[246:249], v3 offset:1024
	s_waitcnt lgkmcnt(2)
	v_mfma_f32_16x16x32_bf16 v[234:237], v[230:233], v[144:147], v[234:237]
	v_mfma_f32_16x16x32_bf16 v[230:233], v[230:233], v[160:163], v[200:203]
	s_nop 2
	ds_read_b128 v[200:203], v3 offset:9216
	s_waitcnt lgkmcnt(2)
	v_mfma_f32_16x16x32_bf16 v[242:245], v[238:241], v[144:147], v[242:245]
	v_mfma_f32_16x16x32_bf16 v[238:241], v[238:241], v[160:163], v[204:207]
	s_waitcnt lgkmcnt(1)
	v_mfma_f32_16x16x32_bf16 v[250:253], v[246:249], v[148:151], v[196:199]
	s_nop 2
	ds_read_b128 v[196:199], v3 offset:17408
	v_mfma_f32_16x16x32_bf16 v[246:249], v[246:249], v[164:167], v[188:191]
	s_nop 2
	ds_read_b128 v[188:191], v3 offset:25600
	s_waitcnt lgkmcnt(2)
	v_mfma_f32_16x16x32_bf16 v[224:227], v[200:203], v[148:151], v[224:227]
	v_mfma_f32_16x16x32_bf16 v[204:207], v[200:203], v[164:167], v[192:195]
	s_waitcnt lgkmcnt(1)
	v_mfma_f32_16x16x32_bf16 v[200:203], v[196:199], v[148:151], v[234:237]
	v_mfma_f32_16x16x32_bf16 v[196:199], v[196:199], v[164:167], v[230:233]
	s_waitcnt lgkmcnt(0)
	v_mfma_f32_16x16x32_bf16 v[192:195], v[188:191], v[148:151], v[242:245]
	v_mfma_f32_16x16x32_bf16 v[188:191], v[188:191], v[164:167], v[238:241]
	v_add_u32_e32 v229, s50, v217
	s_nop 1
	v_add_u32_e32 v238, s50, v218
	ds_read_b64_tr_b16 v[230:231], v229 offset:32768
	ds_read_b64_tr_b16 v[232:233], v229 offset:40960
	ds_read_b64_tr_b16 v[234:235], v238 offset:32768
	ds_read_b64_tr_b16 v[236:237], v238 offset:40960
	v_mfma_f32_16x16x32_bf16 v[68:71], v[220:223], v[184:187], v[68:71]
	v_mov_b32_e32 v239, 0
	v_mov_b32_e32 v240, 0
	v_exp_f32_e32 v2, v250
	v_mfma_f32_16x16x32_bf16 v[132:135], v[220:223], v[180:183], v[132:135]
	v_add_u32_e32 v241, s50, v219
	ds_read_b64_tr_b16 v[220:221], v241 offset:32768
	ds_read_b64_tr_b16 v[222:223], v241 offset:40960
	s_waitcnt lgkmcnt(4)
; #define ATT_SB() __builtin_amdgcn_sched_barrier(0)
; #define A16_VLD(v, g) do { const LAS unsigned char* a_ = vbp[(g) & 3] + vso + ((g) >> 4) * 16384 + (((g) & 15) >> 2) * 1024; v[0] = vtr(a_); v[1] = vtr(a_ + 8192); } while (0)
; #define A16_GAP(i) do { A16_EL(i) = __builtin_amdgcn_exp2f(A16_EL(i)); \
;                 if ((i) > 0) { if ((((i) - 1) >> 2) & 1) s1 += A16_EL((i) - 1); else s0 += A16_EL((i) - 1); } asm volatile("" : "+v"(s0), "+v"(s1)); } while (0)
; __device__ __forceinline__ void attn_core16(f32x4 (&O)[16][2], float (&lq)[2], const bf16_t* Qw, int q_pitch, const bf16_t* Kh, const bf16_t* Vh, int kv_pitch,
;                                             int NT, int nt_act, int kch0, float negb, LAS unsigned char* ring, int wid) {
;     ...
;             A16_VLD(vv[0], 0);
;             ATT_SB();
;             A16_QK(t + 1, 1, t);
;             ATT_SB();
;             A16_VLD(vv[1], 1);
;             float s0 = 0.f, s1 = 0.f;
;     ...
; #pragma unroll
;             for (int g = 0; g < 32; ++g) {
;                 if (g + 2 < 32) A16_VLD(vv[(g + 2) % 3], g + 2);
;                 ATT_SB();
;                 O[g & 15][0] = __builtin_amdgcn_mfma_f32_16x16x32_bf16(A16_VF(vv[g % 3]), __builtin_bit_cast(bf16x8, pw[g >> 4][0]), O[g & 15][0], 0, 0, 0);
;                 O[g & 15][1] = __builtin_amdgcn_mfma_f32_16x16x32_bf16(A16_VF(vv[g % 3]), __builtin_bit_cast(bf16x8, pw[g >> 4][1]), O[g & 15][1], 0, 0, 0);
;                 A16_GAP(g);
;                 ATT_SB();
;             }
	v_mfma_f32_16x16x32_bf16 v[128:131], v[230:233], v[180:183], v[128:131]
	v_add_f32_e32 v239, v2, v239
	v_exp_f32_e32 v3, v251
	v_mfma_f32_16x16x32_bf16 v[64:67], v[230:233], v[184:187], v[64:67]
	ds_read_b64_tr_b16 v[230:231], v0 offset:33792
	ds_read_b64_tr_b16 v[232:233], v0 offset:41984
	s_waitcnt lgkmcnt(4)
	v_mfma_f32_16x16x32_bf16 v[60:63], v[234:237], v[184:187], v[60:63]
	v_add_f32_e32 v239, v3, v239
	v_exp_f32_e32 v242, v252
	v_mfma_f32_16x16x32_bf16 v[124:127], v[234:237], v[180:183], v[124:127]
	ds_read_b64_tr_b16 v[234:235], v229 offset:33792
	ds_read_b64_tr_b16 v[236:237], v229 offset:41984
	s_waitcnt lgkmcnt(4)
	v_mfma_f32_16x16x32_bf16 v[120:123], v[220:223], v[180:183], v[120:123]
	v_add_f32_e32 v239, v242, v239
	v_exp_f32_e32 v243, v253
	v_mfma_f32_16x16x32_bf16 v[56:59], v[220:223], v[184:187], v[56:59]
	ds_read_b64_tr_b16 v[220:221], v238 offset:33792
	ds_read_b64_tr_b16 v[222:223], v238 offset:41984
	s_waitcnt lgkmcnt(4)
	v_mfma_f32_16x16x32_bf16 v[52:55], v[230:233], v[184:187], v[52:55]
	v_add_f32_e32 v239, v243, v239
	v_exp_f32_e32 v244, v246
	v_mfma_f32_16x16x32_bf16 v[116:119], v[230:233], v[180:183], v[116:119]
	ds_read_b64_tr_b16 v[230:231], v241 offset:33792
	ds_read_b64_tr_b16 v[232:233], v241 offset:41984
	s_waitcnt lgkmcnt(4)
	v_mfma_f32_16x16x32_bf16 v[112:115], v[234:237], v[180:183], v[112:115]
	v_add_f32_e32 v240, v244, v240
	v_exp_f32_e32 v245, v247
	v_mfma_f32_16x16x32_bf16 v[48:51], v[234:237], v[184:187], v[48:51]
	ds_read_b64_tr_b16 v[234:235], v0 offset:34816
	ds_read_b64_tr_b16 v[236:237], v0 offset:43008
	s_waitcnt lgkmcnt(4)
	v_mfma_f32_16x16x32_bf16 v[44:47], v[220:223], v[184:187], v[44:47]
	v_add_f32_e32 v240, v245, v240
	v_exp_f32_e32 v246, v248
	v_mfma_f32_16x16x32_bf16 v[108:111], v[220:223], v[180:183], v[108:111]
	ds_read_b64_tr_b16 v[220:221], v229 offset:34816
	ds_read_b64_tr_b16 v[222:223], v229 offset:43008
	s_waitcnt lgkmcnt(4)
	v_mfma_f32_16x16x32_bf16 v[104:107], v[230:233], v[180:183], v[104:107]
	v_add_f32_e32 v240, v246, v240
	v_exp_f32_e32 v247, v249
	v_mfma_f32_16x16x32_bf16 v[40:43], v[230:233], v[184:187], v[40:43]
	ds_read_b64_tr_b16 v[230:231], v238 offset:34816
	ds_read_b64_tr_b16 v[232:233], v238 offset:43008
	s_waitcnt lgkmcnt(4)
	v_mfma_f32_16x16x32_bf16 v[36:39], v[234:237], v[184:187], v[36:39]
	v_add_f32_e32 v240, v247, v240
	v_exp_f32_e32 v248, v224
	v_mfma_f32_16x16x32_bf16 v[100:103], v[234:237], v[180:183], v[100:103]
	ds_read_b64_tr_b16 v[234:235], v241 offset:34816
	ds_read_b64_tr_b16 v[236:237], v241 offset:43008
	s_waitcnt lgkmcnt(4)
	v_mfma_f32_16x16x32_bf16 v[96:99], v[220:223], v[180:183], v[96:99]
	v_add_f32_e32 v224, v248, v239
	v_exp_f32_e32 v249, v225
	v_mfma_f32_16x16x32_bf16 v[32:35], v[220:223], v[184:187], v[32:35]
	ds_read_b64_tr_b16 v[220:221], v0 offset:35840
	ds_read_b64_tr_b16 v[222:223], v0 offset:44032
	s_waitcnt lgkmcnt(4)
	v_mfma_f32_16x16x32_bf16 v[28:31], v[230:233], v[184:187], v[28:31]
	v_add_f32_e32 v224, v249, v224
	v_exp_f32_e32 v239, v226
	v_mfma_f32_16x16x32_bf16 v[92:95], v[230:233], v[180:183], v[92:95]
	ds_read_b64_tr_b16 v[230:231], v229 offset:35840
	ds_read_b64_tr_b16 v[232:233], v229 offset:44032
	s_waitcnt lgkmcnt(4)
	v_mfma_f32_16x16x32_bf16 v[88:91], v[234:237], v[180:183], v[88:91]
	v_add_f32_e32 v251, v239, v224
	v_exp_f32_e32 v250, v227
	v_mfma_f32_16x16x32_bf16 v[24:27], v[234:237], v[184:187], v[24:27]
	ds_read_b64_tr_b16 v[224:225], v238 offset:35840
	ds_read_b64_tr_b16 v[226:227], v238 offset:44032
	s_waitcnt lgkmcnt(4)
	v_mfma_f32_16x16x32_bf16 v[20:23], v[220:223], v[184:187], v[20:23]
	v_exp_f32_e32 v234, v204
	v_add_f32_e32 v204, v250, v251
	v_mfma_f32_16x16x32_bf16 v[84:87], v[220:223], v[180:183], v[84:87]
	ds_read_b64_tr_b16 v[220:221], v241 offset:35840
	ds_read_b64_tr_b16 v[222:223], v241 offset:44032
	s_waitcnt lgkmcnt(4)
	v_mfma_f32_16x16x32_bf16 v[80:83], v[230:233], v[180:183], v[80:83]
	v_exp_f32_e32 v235, v205
	v_add_f32_e32 v205, v234, v240
	v_mfma_f32_16x16x32_bf16 v[16:19], v[230:233], v[184:187], v[16:19]
	ds_read_b64_tr_b16 v[230:231], v0 offset:49152
	ds_read_b64_tr_b16 v[232:233], v0 offset:57344
	s_waitcnt lgkmcnt(4)
	v_mfma_f32_16x16x32_bf16 v[12:15], v[224:227], v[184:187], v[12:15]
	v_add_f32_e32 v205, v235, v205
	v_exp_f32_e32 v236, v206
	v_mfma_f32_16x16x32_bf16 v[76:79], v[224:227], v[180:183], v[76:79]
	ds_read_b64_tr_b16 v[224:225], v229 offset:49152
	ds_read_b64_tr_b16 v[226:227], v229 offset:57344
	s_waitcnt lgkmcnt(4)
	v_mfma_f32_16x16x32_bf16 v[8:11], v[220:223], v[184:187], v[8:11]
	v_add_f32_e32 v184, v236, v205
	v_exp_f32_e32 v237, v207
	v_mfma_f32_16x16x32_bf16 v[72:75], v[220:223], v[180:183], v[72:75]
	ds_read_b64_tr_b16 v[180:181], v238 offset:49152
	ds_read_b64_tr_b16 v[182:183], v238 offset:57344
	s_waitcnt lgkmcnt(4)
	v_mfma_f32_16x16x32_bf16 v[68:71], v[230:233], v[176:179], v[68:71]
	v_add_f32_e32 v221, v237, v184
	v_exp_f32_e32 v220, v200
	v_mfma_f32_16x16x32_bf16 v[132:135], v[230:233], v[172:175], v[132:135]
	ds_read_b64_tr_b16 v[184:185], v241 offset:49152
	ds_read_b64_tr_b16 v[186:187], v241 offset:57344
	s_waitcnt lgkmcnt(4)
; #define ATT_SB() __builtin_amdgcn_sched_barrier(0)
; #define A16_PACK() do { _Pragma("unroll") for (int p_ = 0; p_ < 2; ++p_) _Pragma("unroll") for (int h_ = 0; h_ < 2; ++h_) \
;         pw[p_][h_] = (u32x4){pk2(S[2 * p_][h_][0], S[2 * p_][h_][1]), pk2(S[2 * p_][h_][2], S[2 * p_][h_][3]), pk2(S[2 * p_ + 1][h_][0], S[2 * p_ + 1][h_][1]), pk2(S[2 * p_ + 1][h_][2], S[2 * p_ + 1][h_][3])}; } while (0)
; #define A16_VLD(v, g) do { const LAS unsigned char* a_ = vbp[(g) & 3] + vso + ((g) >> 4) * 16384 + (((g) & 15) >> 2) * 1024; v[0] = vtr(a_); v[1] = vtr(a_ + 8192); } while (0)
; #define A16_GAP(i) do { A16_EL(i) = __builtin_amdgcn_exp2f(A16_EL(i)); \
;                 if ((i) > 0) { if ((((i) - 1) >> 2) & 1) s1 += A16_EL((i) - 1); else s0 += A16_EL((i) - 1); } asm volatile("" : "+v"(s0), "+v"(s1)); } while (0)
; __device__ __forceinline__ void attn_core16(f32x4 (&O)[16][2], float (&lq)[2], const bf16_t* Qw, int q_pitch, const bf16_t* Kh, const bf16_t* Vh, int kv_pitch,
;                                             int NT, int nt_act, int kch0, float negb, LAS unsigned char* ring, int wid) {
;     ...
; #pragma unroll
;             for (int g = 0; g < 32; ++g) {
;                 if (g + 2 < 32) A16_VLD(vv[(g + 2) % 3], g + 2);
;                 ATT_SB();
;                 O[g & 15][0] = __builtin_amdgcn_mfma_f32_16x16x32_bf16(A16_VF(vv[g % 3]), __builtin_bit_cast(bf16x8, pw[g >> 4][0]), O[g & 15][0], 0, 0, 0);
;                 O[g & 15][1] = __builtin_amdgcn_mfma_f32_16x16x32_bf16(A16_VF(vv[g % 3]), __builtin_bit_cast(bf16x8, pw[g >> 4][1]), O[g & 15][1], 0, 0, 0);
;                 A16_GAP(g);
;                 ATT_SB();
;             }
;     ...
;             l0 += more ? s0 : 0.f; l1 += more ? (s1 + A16_EL(31)) : 0.f;
;             A16_PACK();
	v_mfma_f32_16x16x32_bf16 v[128:131], v[224:227], v[172:175], v[128:131]
	v_add_f32_e32 v200, v220, v204
	v_exp_f32_e32 v222, v201
	v_mfma_f32_16x16x32_bf16 v[64:67], v[224:227], v[176:179], v[64:67]
	ds_read_b64_tr_b16 v[204:205], v0 offset:50176
	ds_read_b64_tr_b16 v[206:207], v0 offset:58368
	s_waitcnt lgkmcnt(4)
	v_mfma_f32_16x16x32_bf16 v[60:63], v[180:183], v[176:179], v[60:63]
	v_add_f32_e32 v200, v222, v200
	v_exp_f32_e32 v223, v202
	v_mfma_f32_16x16x32_bf16 v[124:127], v[180:183], v[172:175], v[124:127]
	ds_read_b64_tr_b16 v[180:181], v229 offset:50176
	ds_read_b64_tr_b16 v[182:183], v229 offset:58368
	s_waitcnt lgkmcnt(4)
	v_mfma_f32_16x16x32_bf16 v[120:123], v[184:187], v[172:175], v[120:123]
	v_add_f32_e32 v200, v223, v200
	v_exp_f32_e32 v224, v203
	v_mfma_f32_16x16x32_bf16 v[56:59], v[184:187], v[176:179], v[56:59]
	ds_read_b64_tr_b16 v[184:185], v238 offset:50176
	ds_read_b64_tr_b16 v[186:187], v238 offset:58368
	s_waitcnt lgkmcnt(4)
	v_mfma_f32_16x16x32_bf16 v[52:55], v[204:207], v[176:179], v[52:55]
	v_add_f32_e32 v226, v224, v200
	v_exp_f32_e32 v225, v196
	v_mfma_f32_16x16x32_bf16 v[116:119], v[204:207], v[172:175], v[116:119]
	ds_read_b64_tr_b16 v[200:201], v241 offset:50176
	ds_read_b64_tr_b16 v[202:203], v241 offset:58368
	s_waitcnt lgkmcnt(4)
	v_mfma_f32_16x16x32_bf16 v[112:115], v[180:183], v[172:175], v[112:115]
	v_add_f32_e32 v196, v225, v221
	v_exp_f32_e32 v204, v197
	v_mfma_f32_16x16x32_bf16 v[48:51], v[180:183], v[176:179], v[48:51]
	ds_read_b64_tr_b16 v[180:181], v0 offset:51200
	ds_read_b64_tr_b16 v[182:183], v0 offset:59392
	s_waitcnt lgkmcnt(4)
	v_mfma_f32_16x16x32_bf16 v[44:47], v[184:187], v[176:179], v[44:47]
	v_add_f32_e32 v196, v204, v196
	v_exp_f32_e32 v205, v198
	v_mfma_f32_16x16x32_bf16 v[108:111], v[184:187], v[172:175], v[108:111]
	ds_read_b64_tr_b16 v[184:185], v229 offset:51200
	ds_read_b64_tr_b16 v[186:187], v229 offset:59392
	s_waitcnt lgkmcnt(4)
	v_mfma_f32_16x16x32_bf16 v[104:107], v[200:203], v[172:175], v[104:107]
	v_add_f32_e32 v207, v205, v196
	v_exp_f32_e32 v206, v199
	v_mfma_f32_16x16x32_bf16 v[40:43], v[200:203], v[176:179], v[40:43]
	ds_read_b64_tr_b16 v[196:197], v238 offset:51200
	ds_read_b64_tr_b16 v[198:199], v238 offset:59392
	s_waitcnt lgkmcnt(4)
	v_mfma_f32_16x16x32_bf16 v[36:39], v[180:183], v[176:179], v[36:39]
	v_add_f32_e32 v200, v206, v207
	v_exp_f32_e32 v192, v192
	v_mfma_f32_16x16x32_bf16 v[100:103], v[180:183], v[172:175], v[100:103]
	ds_read_b64_tr_b16 v[180:181], v241 offset:51200
	ds_read_b64_tr_b16 v[182:183], v241 offset:59392
	s_waitcnt lgkmcnt(4)
	v_mfma_f32_16x16x32_bf16 v[96:99], v[184:187], v[172:175], v[96:99]
	v_add_f32_e32 v201, v192, v226
	v_exp_f32_e32 v193, v193
	v_mfma_f32_16x16x32_bf16 v[32:35], v[184:187], v[176:179], v[32:35]
	ds_read_b64_tr_b16 v[184:185], v0 offset:52224
	ds_read_b64_tr_b16 v[186:187], v0 offset:60416
	s_waitcnt lgkmcnt(4)
	v_mfma_f32_16x16x32_bf16 v[28:31], v[196:199], v[176:179], v[28:31]
	v_exp_f32_e32 v0, v194
	v_add_f32_e32 v194, v193, v201
	v_mfma_f32_16x16x32_bf16 v[92:95], v[196:199], v[172:175], v[92:95]
	ds_read_b64_tr_b16 v[196:197], v229 offset:52224
	ds_read_b64_tr_b16 v[198:199], v229 offset:60416
	s_waitcnt lgkmcnt(4)
	v_mfma_f32_16x16x32_bf16 v[88:91], v[180:183], v[172:175], v[88:91]
	v_add_f32_e32 v194, v0, v194
	v_exp_f32_e32 v195, v195
	v_mfma_f32_16x16x32_bf16 v[24:27], v[180:183], v[176:179], v[24:27]
	ds_read_b64_tr_b16 v[180:181], v238 offset:52224
	ds_read_b64_tr_b16 v[182:183], v238 offset:60416
	s_waitcnt lgkmcnt(4)
	v_mfma_f32_16x16x32_bf16 v[20:23], v[184:187], v[176:179], v[20:23]
	v_exp_f32_e32 v201, v188
	v_add_f32_e32 v188, v195, v194
	v_mfma_f32_16x16x32_bf16 v[84:87], v[184:187], v[172:175], v[84:87]
	ds_read_b64_tr_b16 v[184:185], v241 offset:52224
	ds_read_b64_tr_b16 v[186:187], v241 offset:60416
	s_waitcnt lgkmcnt(4)
	v_mfma_f32_16x16x32_bf16 v[80:83], v[196:199], v[172:175], v[80:83]
	v_exp_f32_e32 v194, v189
	v_add_f32_e32 v189, v201, v200
	v_mfma_f32_16x16x32_bf16 v[16:19], v[196:199], v[176:179], v[16:19]
	s_waitcnt lgkmcnt(2)
	v_mfma_f32_16x16x32_bf16 v[12:15], v[180:183], v[176:179], v[12:15]
	v_add_f32_e32 v189, v194, v189
	v_exp_f32_e32 v190, v190
	v_mfma_f32_16x16x32_bf16 v[76:79], v[180:183], v[172:175], v[76:79]
	s_waitcnt lgkmcnt(0)
	v_mfma_f32_16x16x32_bf16 v[8:11], v[184:187], v[176:179], v[8:11]
	v_add_f32_e32 v176, v190, v189
	v_exp_f32_e32 v191, v191
	v_mfma_f32_16x16x32_bf16 v[72:75], v[184:187], v[172:175], v[72:75]
	s_cmp_lt_u32 s20, s73
	v_add_f32_e32 v172, v191, v176
	s_cselect_b64 vcc, -1, 0
	v_cndmask_b32_e32 v189, 0, v188, vcc
	v_cndmask_b32_e32 v188, 0, v172, vcc
	v_cvt_pk_bf16_f32 v184, v2, v3
	v_cvt_pk_bf16_f32 v185, v242, v243
	v_cvt_pk_bf16_f32 v186, v248, v249
	v_cvt_pk_bf16_f32 v187, v239, v250
	v_cvt_pk_bf16_f32 v180, v244, v245
	v_cvt_pk_bf16_f32 v181, v246, v247
	v_cvt_pk_bf16_f32 v182, v234, v235
	v_cvt_pk_bf16_f32 v183, v236, v237
	v_cvt_pk_bf16_f32 v176, v220, v222
	v_cvt_pk_bf16_f32 v177, v223, v224
	v_cvt_pk_bf16_f32 v178, v192, v193
	v_cvt_pk_bf16_f32 v179, v0, v195
	v_cvt_pk_bf16_f32 v172, v225, v204
	v_cvt_pk_bf16_f32 v173, v205, v206
	v_cvt_pk_bf16_f32 v174, v201, v194
	v_cvt_pk_bf16_f32 v175, v190, v191
	v_pk_add_f32 v[208:209], v[208:209], v[188:189]
